# RWKV state recurrence: a chunk's outputs are written to LDS before the next record's fragment reads are issued and the step barrier waits only for those writes (counted lgkmcnt), so the fragment reads
# baseline (speedup 1.0000x reference)
.LBB0_433:
	s_mul_i32 s1, s0, 37
	s_bfe_u32 s2, s1, 0x80008
	s_lshr_b32 s1, s1, 8
	s_sub_i32 s1, s0, s1
	s_bfe_u32 s1, s1, 0x70001
	s_add_i32 s1, s1, s2
	s_bfe_u32 s1, s1, 0x60002
	s_mul_i32 s1, s1, 7
	s_sub_i32 s1, s0, s1
	s_and_b32 s1, s1, 0xff
	s_mulk_i32 s1, 0x4800
	v_add_u32_e32 v136, s1, v151
	v_cvt_pk_bf16_f32 v112, v16, v17
	v_cvt_pk_bf16_f32 v113, v18, v19
	v_cvt_pk_bf16_f32 v114, v20, v21
	v_cvt_pk_bf16_f32 v115, v22, v23
	v_cvt_pk_bf16_f32 v116, v24, v25
	v_cvt_pk_bf16_f32 v117, v26, v27
	v_cvt_pk_bf16_f32 v118, v28, v29
	v_cvt_pk_bf16_f32 v119, v30, v31
	v_cvt_pk_bf16_f32 v120, v0, v1
	v_cvt_pk_bf16_f32 v121, v2, v3
	v_cvt_pk_bf16_f32 v122, v4, v5
	v_cvt_pk_bf16_f32 v123, v6, v7
	v_cvt_pk_bf16_f32 v124, v8, v9
	v_cvt_pk_bf16_f32 v125, v10, v11
	v_cvt_pk_bf16_f32 v126, v12, v13
	v_cvt_pk_bf16_f32 v127, v14, v15
	ds_read_b128 v[32:35], v136 offset:17792
	ds_read_b128 v[36:39], v136 offset:17824
	ds_read_b128 v[40:43], v136 offset:17856
	ds_read_b128 v[128:131], v136 offset:17920
	ds_read_b128 v[132:135], v136 offset:17952
	s_waitcnt lgkmcnt(0)
	v_pk_mul_f32 v[16:17], v[16:17], v[32:33]
	v_pk_mul_f32 v[18:19], v[18:19], v[34:35]
	ds_read_b128 v[32:35], v136 offset:17888
	v_pk_mul_f32 v[20:21], v[20:21], v[36:37]
	v_pk_mul_f32 v[22:23], v[22:23], v[38:39]
	v_pk_mul_f32 v[24:25], v[24:25], v[40:41]
	v_pk_mul_f32 v[26:27], v[26:27], v[42:43]
	s_waitcnt lgkmcnt(0)
	v_pk_mul_f32 v[28:29], v[28:29], v[32:33]
	v_pk_mul_f32 v[30:31], v[30:31], v[34:35]
	v_mfma_f32_32x32x16_bf16 v[32:47], v[48:51], v[112:115], 0
	v_mul_f32_e64 v0, v0, v128
	v_mul_f32_e64 v1, v1, v129
	v_mul_f32_e64 v2, v2, v130
	v_mul_f32_e64 v3, v3, v131
	v_mul_f32_e64 v4, v4, v132
	v_mul_f32_e64 v5, v5, v133
	v_pk_mul_f32 v[6:7], v[6:7], v[134:135]
	ds_read_b128 v[128:131], v136 offset:17984
	ds_read_b128 v[132:135], v136 offset:18016
	s_or_b32 s1, s0, 1
	v_mfma_f32_32x32x16_bf16 v[16:31], v[72:75], v[112:115], v[16:31]
	s_and_b32 s2, s1, 0xff
	s_waitcnt lgkmcnt(0)
	v_mul_f32_e64 v8, v8, v128
	v_mul_f32_e64 v9, v9, v129
	v_mul_f32_e64 v10, v10, v130
	v_mul_f32_e64 v11, v11, v131
	v_pk_mul_f32 v[12:13], v[12:13], v[132:133]
	v_pk_mul_f32 v[14:15], v[14:15], v[134:135]
	s_mul_i32 s2, s2, 37
	s_lshr_b32 s2, s2, 8
	v_mfma_f32_32x32x16_bf16 v[32:47], v[52:55], v[116:119], v[32:47]
	s_sub_i32 s3, s1, s2
	s_bfe_u32 s3, s3, 0x70001
	s_add_i32 s3, s3, s2
	s_lshr_b32 s2, s3, 2
	s_mul_i32 s2, s2, 7
	s_sub_i32 s1, s1, s2
	s_and_b32 s1, s1, 0xff
	v_mfma_f32_32x32x16_bf16 v[0:15], v[88:91], v[112:115], v[0:15]
	s_mulk_i32 s1, 0x4800
	s_add_i32 s1, s1, 0
	v_add_u32_e32 v192, s1, v144
	v_add_u32_e32 v180, v192, v156
	s_cmpk_gt_u32 s0, 0x7d
	s_cselect_b64 s[2:3], -1, 0
	v_mfma_f32_32x32x16_bf16 v[16:31], v[76:79], v[116:119], v[16:31]
	s_and_b64 vcc, exec, s[2:3]
	v_mfma_f32_32x32x16_bf16 v[32:47], v[56:59], v[120:123], v[32:47]
	v_mfma_f32_32x32x16_bf16 v[0:15], v[92:95], v[116:119], v[0:15]
	v_mfma_f32_32x32x16_bf16 v[16:31], v[80:83], v[120:123], v[16:31]
	v_mfma_f32_32x32x16_bf16 v[32:47], v[60:63], v[124:127], v[32:47]
	v_mfma_f32_32x32x16_bf16 v[0:15], v[96:99], v[120:123], v[0:15]
	v_mfma_f32_32x32x16_bf16 v[16:31], v[84:87], v[124:127], v[16:31]
	v_mfma_f32_32x32x16_bf16 v[32:47], v[68:71], v[64:67], v[32:47]
	v_mfma_f32_32x32x16_bf16 v[0:15], v[100:103], v[124:127], v[0:15]
	s_nop 10
	ds_write2st64_b32 v158, v32, v33 offset1:1
	ds_write2st64_b32 v158, v34, v35 offset0:2 offset1:3
	ds_write2st64_b32 v158, v36, v37 offset0:8 offset1:9
	ds_write2st64_b32 v158, v38, v39 offset0:10 offset1:11
	v_add_u32_e32 v45, s1, v153
	v_add_u32_e32 v46, v45, v152
	v_add_u32_e32 v160, v45, v155
	v_add_u32_e32 v44, v192, v150
	ds_read2_b64 v[40:43], v46 offset1:2
	ds_read2_b64 v[116:119], v46 offset0:4 offset1:6
	ds_read2_b64 v[120:123], v46 offset0:8 offset1:10
	ds_read2_b64 v[124:127], v46 offset0:12 offset1:14
	v_add_u32_e32 v46, v192, v154
	v_add_u32_e32 v132, 0x800, v160
	v_mfma_f32_32x32x16_bf16 v[16:31], v[104:107], v[64:67], v[16:31]
	v_add_u32_e32 v172, 0x1800, v160
	ds_read_b128 v[112:115], v44 offset:14720
	ds_read_b128 v[128:131], v46 offset:2176
	ds_read2_b64 v[44:47], v132 offset0:112 offset1:114
	ds_read2_b64 v[140:143], v132 offset0:116 offset1:118
	ds_read2_b64 v[136:139], v132 offset0:120 offset1:122
	ds_read2_b64 v[132:135], v132 offset0:124 offset1:126
	ds_read2_b64 v[160:163], v172 offset0:144 offset1:146
	s_waitcnt lgkmcnt(11)
	ds_read2_b64 v[164:167], v172 offset0:148 offset1:150
	ds_read2_b64 v[168:171], v172 offset0:152 offset1:154
	ds_read2_b64 v[172:175], v172 offset0:156 offset1:158
	ds_read_b128 v[176:179], v180 offset:11648
	ds_read_b128 v[180:183], v180 offset:13184
	s_barrier
	v_cvt_pk_bf16_f32 v32, v16, v17
	v_mfma_f32_32x32x16_bf16 v[0:15], v[108:111], v[64:67], v[0:15]
	v_cvt_pk_bf16_f32 v33, v18, v19
	v_cvt_pk_bf16_f32 v34, v20, v21
	v_cvt_pk_bf16_f32 v35, v22, v23
	v_cvt_pk_bf16_f32 v184, v24, v25
	v_cvt_pk_bf16_f32 v185, v26, v27
	v_cvt_pk_bf16_f32 v186, v28, v29
	v_cvt_pk_bf16_f32 v187, v30, v31
	v_cvt_pk_bf16_f32 v188, v0, v1
	v_cvt_pk_bf16_f32 v189, v2, v3
	v_cvt_pk_bf16_f32 v190, v4, v5
	v_cvt_pk_bf16_f32 v191, v6, v7
	v_cvt_pk_bf16_f32 v216, v8, v9
	v_cvt_pk_bf16_f32 v217, v10, v11
	v_cvt_pk_bf16_f32 v218, v12, v13
	v_cvt_pk_bf16_f32 v219, v14, v15
	ds_read_b128 v[36:39], v192 offset:17888
	s_waitcnt lgkmcnt(0)
	v_pk_mul_f32 v[28:29], v[28:29], v[36:37]
	v_pk_mul_f32 v[30:31], v[30:31], v[38:39]
	ds_read_b128 v[36:39], v192 offset:17856
	s_waitcnt lgkmcnt(0)
	v_pk_mul_f32 v[24:25], v[24:25], v[36:37]
	v_pk_mul_f32 v[26:27], v[26:27], v[38:39]
	ds_read_b128 v[36:39], v192 offset:17824
	s_waitcnt lgkmcnt(0)
	v_pk_mul_f32 v[20:21], v[20:21], v[36:37]
	v_pk_mul_f32 v[22:23], v[22:23], v[38:39]
	ds_read_b128 v[36:39], v192 offset:17792
	s_waitcnt lgkmcnt(0)
	v_pk_mul_f32 v[18:19], v[18:19], v[38:39]
	v_pk_mul_f32 v[16:17], v[16:17], v[36:37]
	ds_read_b128 v[36:39], v192 offset:18016
	s_waitcnt lgkmcnt(0)
	v_pk_mul_f32 v[12:13], v[12:13], v[36:37]
	v_pk_mul_f32 v[14:15], v[14:15], v[38:39]
	ds_read_b128 v[36:39], v192 offset:17984
	v_mfma_f32_32x32x16_bf16 v[16:31], v[44:47], v[32:35], v[16:31]
	s_waitcnt lgkmcnt(0)
	v_mul_f32_e64 v8, v8, v36
	v_mul_f32_e64 v9, v9, v37
	v_mul_f32_e64 v10, v10, v38
	v_mul_f32_e64 v11, v11, v39
	ds_read_b128 v[36:39], v192 offset:17952
	s_waitcnt lgkmcnt(0)
	v_pk_mul_f32 v[4:5], v[4:5], v[36:37]
	v_pk_mul_f32 v[6:7], v[6:7], v[38:39]
	ds_read_b128 v[36:39], v192 offset:17920
	v_mfma_f32_32x32x16_bf16 v[16:31], v[140:143], v[184:187], v[16:31]
	s_waitcnt lgkmcnt(0)
	v_mul_f32_e64 v2, v2, v38
	v_mul_f32_e64 v3, v3, v39
	v_mul_f32_e64 v0, v0, v36
	v_mul_f32_e64 v1, v1, v37
	s_nop 1
	v_mfma_f32_32x32x16_bf16 v[0:15], v[160:163], v[32:35], v[0:15]
	v_mfma_f32_32x32x16_bf16 v[32:47], v[40:43], v[32:35], 0
	v_mfma_f32_32x32x16_bf16 v[32:47], v[116:119], v[184:187], v[32:47]
	v_mfma_f32_32x32x16_bf16 v[0:15], v[164:167], v[184:187], v[0:15]
	v_mfma_f32_32x32x16_bf16 v[32:47], v[120:123], v[188:191], v[32:47]
	v_mfma_f32_32x32x16_bf16 v[16:31], v[136:139], v[188:191], v[16:31]
	v_mfma_f32_32x32x16_bf16 v[0:15], v[168:171], v[188:191], v[0:15]
	v_mfma_f32_32x32x16_bf16 v[32:47], v[124:127], v[216:219], v[32:47]
	v_mfma_f32_32x32x16_bf16 v[16:31], v[132:135], v[216:219], v[16:31]
	v_mfma_f32_32x32x16_bf16 v[0:15], v[172:175], v[216:219], v[0:15]
	v_mfma_f32_32x32x16_bf16 v[32:47], v[128:131], v[112:115], v[32:47]
	v_mfma_f32_32x32x16_bf16 v[16:31], v[176:179], v[112:115], v[16:31]
	v_mfma_f32_32x32x16_bf16 v[0:15], v[180:183], v[112:115], v[0:15]
	s_cbranch_vccnz .LBB0_432
	s_add_i32 s1, s0, 2
	s_and_b32 s4, s1, 0xff
	s_mul_i32 s4, s4, 37
	s_lshr_b32 s5, s4, 8
	s_sub_i32 s5, s1, s5
	s_bfe_u32 s5, s5, 0x70001
	s_bfe_u32 s4, s4, 0x80008
	s_add_i32 s5, s5, s4
	s_bfe_u32 s4, s5, 0x60002
	s_mul_i32 s4, s4, 7
	s_sub_i32 s1, s1, s4
	s_and_b32 s1, s1, 0xff
	s_mulk_i32 s1, 0x4800
	s_add_i32 s1, s1, 0
	v_add_u32_e32 v40, s1, v144
	v_add_u32_e32 v42, s1, v153
	v_add_u32_e32 v41, v40, v150
	v_add_u32_e32 v43, v42, v152
	ds_write2st64_b32 v159, v32, v33 offset1:1
	ds_write2st64_b32 v159, v34, v35 offset0:2 offset1:3
	ds_write2st64_b32 v159, v36, v37 offset0:8 offset1:9
	ds_write2st64_b32 v159, v38, v39 offset0:10 offset1:11
	ds_read2_b64 v[48:51], v43 offset1:2
	ds_read2_b64 v[52:55], v43 offset0:4 offset1:6
	ds_read2_b64 v[56:59], v43 offset0:8 offset1:10
	ds_read2_b64 v[60:63], v43 offset0:12 offset1:14
	v_add_u32_e32 v43, v40, v154
	ds_read_b128 v[64:67], v41 offset:14720
	ds_read_b128 v[68:71], v43 offset:2176
	v_add_u32_e32 v41, v42, v155
	v_add_u32_e32 v42, 0x800, v41
	v_add_u32_e32 v41, 0x1800, v41
	ds_read2_b64 v[72:75], v42 offset0:112 offset1:114
	ds_read2_b64 v[76:79], v42 offset0:116 offset1:118
	ds_read2_b64 v[80:83], v42 offset0:120 offset1:122
	ds_read2_b64 v[84:87], v42 offset0:124 offset1:126
	v_add_u32_e32 v40, v40, v156
	ds_read2_b64 v[88:91], v41 offset0:144 offset1:146
	s_waitcnt lgkmcnt(11)
	ds_read2_b64 v[92:95], v41 offset0:148 offset1:150
	ds_read2_b64 v[96:99], v41 offset0:152 offset1:154
	ds_read2_b64 v[100:103], v41 offset0:156 offset1:158
	ds_read_b128 v[104:107], v40 offset:11648
	ds_read_b128 v[108:111], v40 offset:13184
	s_barrier
	s_add_i32 s0, s0, 2
	s_and_b64 vcc, exec, s[2:3]
	s_cbranch_vccnz .LBB0_435
	s_branch .LBB0_433
